# P0 weight transpose (gate/up variant): the 32 folded-gain loads per item issued together with one wait instead of four at a time
# speedup vs baseline: 1.0243x; 1.0056x over previous
.LBB0_12:
	s_andn2_saveexec_b64 s[16:17], s[4:5]
	s_cbranch_execz .LBB0_38
	v_add_u16_e32 v2, 0xf880, v61
	v_mul_u32_u24_e32 v14, 0xba2f, v2
	v_lshrrev_b32_e32 v14, 23, v14
	v_mul_lo_u16_e32 v15, 0xb0, v14
	v_sub_u16_e32 v2, v2, v15
	v_lshlrev_b16_e32 v62, 5, v2
	v_or_b32_e32 v2, v1, v62
	v_lshrrev_b32_e32 v2, 1, v2
	v_lshlrev_b16_e32 v63, 6, v14
	v_and_b32_e32 v14, 0xff0, v2
	v_or_b32_e32 v30, v33, v63
	v_add_u32_e32 v14, v40, v14
	v_and_or_b32 v2, v2, 12, v14
	v_mul_u32_u24_e32 v14, 0x1600, v30
	v_add_lshl_u32 v2, v2, v14, 2
	v_lshl_add_u64 v[14:15], s[72:73], 0, v[2:3]
	v_add_co_u32_e32 v16, vcc, s30, v14
	v_cndmask_b32_e64 v31, 0, 1, s[10:11]
	s_nop 0
	v_addc_co_u32_e32 v17, vcc, 0, v15, vcc
	v_add_co_u32_e32 v18, vcc, s28, v14
	v_cmp_ne_u32_e64 s[4:5], 1, v31
	s_nop 0
	v_addc_co_u32_e32 v19, vcc, 0, v15, vcc
	v_add_co_u32_e32 v20, vcc, s31, v14
	s_nop 1
	v_addc_co_u32_e32 v21, vcc, 0, v15, vcc
	v_add_co_u32_e32 v22, vcc, s29, v14
	s_nop 1
	v_addc_co_u32_e32 v23, vcc, 0, v15, vcc
	v_add_co_u32_e32 v24, vcc, s33, v14
	s_nop 1
	v_addc_co_u32_e32 v25, vcc, 0, v15, vcc
	v_add_co_u32_e32 v26, vcc, s34, v14
	s_nop 1
	v_addc_co_u32_e32 v27, vcc, 0, v15, vcc
	v_add_co_u32_e32 v64, vcc, s35, v14
	s_nop 1
	v_addc_co_u32_e32 v65, vcc, 0, v15, vcc
	v_add_co_u32_e32 v66, vcc, s36, v14
	s_nop 1
	v_addc_co_u32_e32 v67, vcc, 0, v15, vcc
	global_load_dword v78, v[16:17], off
	global_load_dword v28, v[18:19], off
	global_load_dword v29, v[20:21], off
	global_load_dword v76, v[22:23], off
	global_load_dword v77, v[24:25], off
	s_nop 0
	global_load_dword v26, v[26:27], off
	s_nop 0
	global_load_dword v27, v[64:65], off
	global_load_dword v74, v[66:67], off
	v_add_co_u32_e32 v16, vcc, s37, v14
	s_nop 1
	v_addc_co_u32_e32 v17, vcc, 0, v15, vcc
	v_add_co_u32_e32 v18, vcc, s38, v14
	s_nop 1
	v_addc_co_u32_e32 v19, vcc, 0, v15, vcc
	v_add_co_u32_e32 v20, vcc, s39, v14
	s_nop 1
	v_addc_co_u32_e32 v21, vcc, 0, v15, vcc
	v_add_co_u32_e32 v22, vcc, s40, v14
	s_nop 1
	v_addc_co_u32_e32 v23, vcc, 0, v15, vcc
	v_add_co_u32_e32 v64, vcc, s41, v14
	s_nop 1
	v_addc_co_u32_e32 v65, vcc, 0, v15, vcc
	v_add_co_u32_e32 v66, vcc, s42, v14
	s_nop 1
	v_addc_co_u32_e32 v67, vcc, 0, v15, vcc
	v_add_co_u32_e32 v68, vcc, s43, v14
	s_nop 1
	v_addc_co_u32_e32 v69, vcc, 0, v15, vcc
	v_add_co_u32_e32 v70, vcc, s44, v14
	s_nop 1
	v_addc_co_u32_e32 v71, vcc, 0, v15, vcc
	global_load_dword v75, v[16:17], off
	global_load_dword v24, v[18:19], off
	global_load_dword v25, v[20:21], off
	global_load_dword v72, v[22:23], off
	global_load_dword v73, v[64:65], off
	s_nop 0
	global_load_dword v22, v[66:67], off
	global_load_dword v23, v[68:69], off
	s_nop 0
	global_load_dword v70, v[70:71], off
	v_add_co_u32_e32 v16, vcc, s45, v14
	s_nop 1
	v_addc_co_u32_e32 v17, vcc, 0, v15, vcc
	v_add_co_u32_e32 v18, vcc, s46, v14
	s_nop 1
	v_addc_co_u32_e32 v19, vcc, 0, v15, vcc
	v_add_co_u32_e32 v64, vcc, s47, v14
	s_nop 1
	v_addc_co_u32_e32 v65, vcc, 0, v15, vcc
	v_add_co_u32_e32 v66, vcc, s48, v14
	s_nop 1
	v_addc_co_u32_e32 v67, vcc, 0, v15, vcc
	v_add_co_u32_e32 v80, vcc, s49, v14
	s_nop 1
	v_addc_co_u32_e32 v81, vcc, 0, v15, vcc
	v_add_co_u32_e32 v82, vcc, s50, v14
	s_nop 1
	v_addc_co_u32_e32 v83, vcc, 0, v15, vcc
	v_add_co_u32_e32 v84, vcc, s51, v14
	s_nop 1
	v_addc_co_u32_e32 v85, vcc, 0, v15, vcc
	v_add_co_u32_e32 v86, vcc, s52, v14
	s_nop 1
	v_addc_co_u32_e32 v87, vcc, 0, v15, vcc
	global_load_dword v71, v[16:17], off
	global_load_dword v20, v[18:19], off
	global_load_dword v21, v[64:65], off
	global_load_dword v68, v[66:67], off
	global_load_dword v69, v[80:81], off
	s_nop 0
	global_load_dword v18, v[82:83], off
	global_load_dword v19, v[84:85], off
	global_load_dword v65, v[86:87], off
	v_add_co_u32_e32 v16, vcc, s53, v14
	v_add_lshl_u32 v66, v33, v63, 2
	s_nop 0
	v_addc_co_u32_e32 v17, vcc, 0, v15, vcc
	v_add_co_u32_e32 v80, vcc, s54, v14
	s_nop 1
	v_addc_co_u32_e32 v81, vcc, 0, v15, vcc
	v_add_co_u32_e32 v82, vcc, s55, v14
	s_nop 1
	v_addc_co_u32_e32 v83, vcc, 0, v15, vcc
	v_add_co_u32_e32 v84, vcc, s84, v14
	s_nop 1
	v_addc_co_u32_e32 v85, vcc, 0, v15, vcc
	v_add_co_u32_e32 v86, vcc, 0x13f000, v14
	s_nop 1
	v_addc_co_u32_e32 v87, vcc, 0, v15, vcc
	v_add_co_u32_e32 v88, vcc, 0x14a000, v14
	s_nop 1
	v_addc_co_u32_e32 v89, vcc, 0, v15, vcc
	v_add_co_u32_e32 v92, vcc, 0x155000, v14
	s_nop 1
	v_addc_co_u32_e32 v93, vcc, 0, v15, vcc
	global_load_dword v79, v2, s[72:73]
	global_load_dword v67, v[16:17], off
	s_nop 0
	global_load_dword v16, v[80:81], off
	global_load_dword v17, v[82:83], off
	global_load_dword v2, v[84:85], off
	global_load_dword v64, v[86:87], off
	global_load_dword v14, v[88:89], off
	global_load_dword v15, v[92:93], off
	s_andn2_b64 vcc, exec, s[10:11]
	s_cbranch_vccnz .LBB0_44
	v_lshlrev_b32_e32 v30, 2, v30
	global_load_dword v110, v30, s[70:71]
	global_load_dword v111, v66, s[70:71] offset:8
	global_load_dword v94, v66, s[70:71] offset:16
	global_load_dword v95, v66, s[70:71] offset:24
	global_load_dword v112, v66, s[70:71] offset:32
	global_load_dword v113, v66, s[70:71] offset:40
	global_load_dword v96, v66, s[70:71] offset:48
	global_load_dword v97, v66, s[70:71] offset:56
	global_load_dword v114, v66, s[70:71] offset:64
	global_load_dword v115, v66, s[70:71] offset:72
	global_load_dword v98, v66, s[70:71] offset:80
	global_load_dword v99, v66, s[70:71] offset:88
	global_load_dword v116, v66, s[70:71] offset:96
	global_load_dword v117, v66, s[70:71] offset:104
	global_load_dword v100, v66, s[70:71] offset:112
	global_load_dword v101, v66, s[70:71] offset:120
	global_load_dword v166, v66, s[70:71] offset:128
	global_load_dword v167, v66, s[70:71] offset:136
	global_load_dword v102, v66, s[70:71] offset:144
	global_load_dword v103, v66, s[70:71] offset:152
	global_load_dword v168, v66, s[70:71] offset:160
	global_load_dword v169, v66, s[70:71] offset:168
	global_load_dword v104, v66, s[70:71] offset:176
	global_load_dword v105, v66, s[70:71] offset:184
	global_load_dword v170, v66, s[70:71] offset:192
	global_load_dword v171, v66, s[70:71] offset:200
	global_load_dword v106, v66, s[70:71] offset:208
	global_load_dword v107, v66, s[70:71] offset:216
	global_load_dword v172, v66, s[70:71] offset:224
	global_load_dword v173, v66, s[70:71] offset:232
	global_load_dword v108, v66, s[70:71] offset:240
	global_load_dword v109, v66, s[70:71] offset:248
	s_waitcnt vmcnt(0)
	s_nop 0
	v_mul_f32_e32 v80, v79, v110
	v_mul_f32_e32 v81, v78, v111
	ds_write_b32 v34, v80
	ds_write_b32 v58, v81
	v_pk_mul_f32 v[30:31], v[28:29], v[94:95]
	s_cbranch_execnz .LBB0_16

.LBB0_16:
	s_and_b64 vcc, exec, s[4:5]
	ds_write2_b32 v49, v30, v31 offset1:66
	s_cbranch_vccnz .LBB0_45
	v_mul_f32_e32 v30, v76, v112
	v_mul_f32_e32 v31, v77, v113
	ds_write2_b32 v59, v30, v31 offset1:66
	v_pk_mul_f32 v[28:29], v[26:27], v[96:97]
	s_cbranch_execnz .LBB0_19

.LBB0_19:
	s_and_b64 vcc, exec, s[4:5]
	s_waitcnt vmcnt(29)
	ds_write2_b32 v50, v28, v29 offset1:66
	s_cbranch_vccnz .LBB0_46
	v_mul_f32_e32 v28, v74, v114
	v_mul_f32_e32 v29, v75, v115
	ds_write2_b32 v60, v28, v29 offset1:66
	v_pk_mul_f32 v[26:27], v[24:25], v[98:99]
	s_cbranch_execnz .LBB0_22

.LBB0_22:
	s_waitcnt vmcnt(25)
	ds_write2_b32 v60, v26, v27 offset0:132 offset1:198
	s_and_b64 vcc, exec, s[4:5]
	v_add_u32_e32 v26, 0x400, v60
	s_cbranch_vccnz .LBB0_47
	v_mul_f32_e32 v27, v72, v116
	v_mul_f32_e32 v28, v73, v117
	ds_write2_b32 v26, v27, v28 offset0:8 offset1:74
	v_pk_mul_f32 v[24:25], v[22:23], v[100:101]
	s_cbranch_execnz .LBB0_25

.LBB0_25:
	s_waitcnt vmcnt(21)
	ds_write2_b32 v26, v24, v25 offset0:140 offset1:206
	s_and_b64 vcc, exec, s[4:5]
	v_add_u32_e32 v24, 0x800, v60
	s_cbranch_vccnz .LBB0_48
	v_mul_f32_e32 v25, v70, v166
	v_mul_f32_e32 v26, v71, v167
	ds_write2_b32 v24, v25, v26 offset0:16 offset1:82
	v_pk_mul_f32 v[22:23], v[20:21], v[102:103]
	s_cbranch_execnz .LBB0_28

.LBB0_28:
	s_waitcnt vmcnt(17)
	ds_write2_b32 v24, v22, v23 offset0:148 offset1:214
	s_and_b64 vcc, exec, s[4:5]
	v_add_u32_e32 v22, 0xc00, v60
	s_cbranch_vccnz .LBB0_49
	v_mul_f32_e32 v23, v68, v168
	v_mul_f32_e32 v24, v69, v169
	ds_write2_b32 v22, v23, v24 offset0:24 offset1:90
	v_pk_mul_f32 v[20:21], v[18:19], v[104:105]
	s_cbranch_execnz .LBB0_31

.LBB0_31:
	s_waitcnt vmcnt(13)
	ds_write2_b32 v22, v20, v21 offset0:156 offset1:222
	s_and_b64 vcc, exec, s[4:5]
	v_add_u32_e32 v20, 0x1000, v60
	s_cbranch_vccnz .LBB0_50
	v_mul_f32_e32 v21, v65, v170
	v_mul_f32_e32 v22, v67, v171
	ds_write2_b32 v20, v21, v22 offset0:32 offset1:98
	v_pk_mul_f32 v[18:19], v[16:17], v[106:107]
	s_cbranch_execnz .LBB0_34

.LBB0_34:
	s_waitcnt vmcnt(9)
	ds_write2_b32 v20, v18, v19 offset0:164 offset1:230
	s_and_b64 vcc, exec, s[4:5]
	v_add_u32_e32 v18, 0x1400, v60
	s_cbranch_vccnz .LBB0_51
	v_mul_f32_e32 v19, v2, v172
	v_mul_f32_e32 v20, v64, v173
	ds_write2_b32 v18, v19, v20 offset0:40 offset1:106
	v_pk_mul_f32 v[16:17], v[14:15], v[108:109]
	s_cbranch_execnz .LBB0_37
